# GEMM K-loop LDS-DMA addressing: SGPR base + 32-bit VGPR offset instead of a 64-bit VALU add per DMA (16 VALU ops per iteration removed), LDS stage offsets as literals
# baseline (speedup 1.0000x reference)
; #define PG8_STAGE(bufoff, gbase, voff) do { _Pragma("unroll") for (int _i = 0; _i < 2; ++_i) \
;         __builtin_amdgcn_global_load_lds((const unsigned*)((const char*)(gbase) + (voff)[_i]), (LAS unsigned*)(lds + (bufoff) + ldsw + _i * 8192), 16, 0, 0); } while (0)
; #define PG8_LDA(dst, b, h) do { _Pragma("unroll") for (int m = 0; m < 4; ++m) _Pragma("unroll") for (int k = 0; k < 2; ++k) dst[m][k] = *(const LAS bf16x8*)(lds + PG8_SA(b, h) + aoff + m * 2048 + k * 1024); } while (0)
; #define PG8_LDB(dst, b, h) do { _Pragma("unroll") for (int n = 0; n < 2; ++n) _Pragma("unroll") for (int k = 0; k < 2; ++k) dst[n][k] = *(const LAS bf16x8*)(lds + PG8_SB(b, h) + boff + n * 2048 + k * 1024); } while (0)
; #define PG8_MMA(ai, bj, At, Bt) do { __builtin_amdgcn_s_setprio(1); _Pragma("unroll") for (int m = 0; m < 4; ++m) _Pragma("unroll") for (int n = 0; n < 2; ++n) _Pragma("unroll") for (int k = 0; k < 2; ++k) \
;         acc[ai][bj][m][n] = __builtin_amdgcn_mfma_f32_16x16x32_bf16(Bt[n][k], At[m][k], acc[ai][bj][m][n], 0, 0, 0); __builtin_amdgcn_s_setprio(0); } while (0)
; #define PG8_WAIT_V(n) asm volatile("s_waitcnt vmcnt(" #n ")" ::: "memory")
; #define PG8_WAIT_L(n) asm volatile("s_waitcnt lgkmcnt(" #n ")" ::: "memory")
; #define PG8_BAR __builtin_amdgcn_s_barrier()
; __device__ __forceinline__ void gemm_phase(LAS unsigned char* lds, CParams& p, const Job& jb) {
;     ...
;         for (int t = 0; t < nt; t += 2) {
;             const bool last = (t == nt - 2);
;             const char* a1 = cA + (size_t)(t + 1) * kstep;
;             const char* a2 = last ? nA : cA + (size_t)(t + 2) * kstep; const char* b2 = last ? nB : cB + (size_t)(t + 2) * kstep;
;             const char* a3 = a2 + kstep; const char* b3 = b2 + kstep;
;             PG8_LDB(B0, 0, 0); PG8_SCHED; PG8_LDA(At, 0, 0); PG8_STAGE(PG8_SA(1, 1), a1 + hstepA, voffA);
;             PG8_WAIT_L(8); PG8_BAR; PG8_WAIT_L(0); PG8_MMA(0, 0, At, B0); PG8_BAR; PG8_SCHED;
;             PG8_LDB(B1, 0, 1); PG8_STAGE(PG8_SB(0, 0), b2, voffB);
;             PG8_BAR; PG8_WAIT_L(0); PG8_MMA(0, 1, At, B1); PG8_BAR;
;             PG8_LDA(At, 0, 1); PG8_STAGE(PG8_SA(0, 0), a2, voffA);
;             PG8_BAR; PG8_WAIT_L(0); PG8_MMA(1, 0, At, B0); PG8_BAR; PG8_SCHED;
;             PG8_STAGE(PG8_SB(0, 1), b2 + hstepB, voffB);
;             PG8_WAIT_V(6); PG8_BAR; PG8_MMA(1, 1, At, B1); PG8_BAR;
.LBB0_631:
	s_add_i32 s1, s1, 2
	s_add_u32 s12, s24, s10
	s_addc_u32 s13, s25, s11
	s_add_u32 s12, s12, 0x100
	s_addc_u32 s13, s13, 0
	s_add_u32 s14, s97, s10
	s_addc_u32 s15, s2, s11
	s_add_u32 s100, s24, s10
	s_addc_u32 s101, s25, s11
	s_add_u32 s100, s100, 0x80
	s_addc_u32 s101, s101, 0
	v_add_u32_e32 v144, 0x10000, v213
	ds_read_b128 v[132:135], v144
	ds_read_b128 v[136:139], v144 offset:1024
	ds_read_b128 v[140:143], v144 offset:2048
	ds_read_b128 v[144:147], v144 offset:3072
	s_cmp_eq_u32 s85, s10
	s_cselect_b32 s13, s5, s13
	s_cselect_b32 s12, s4, s12
	s_cselect_b32 s15, s87, s15
	s_cselect_b32 s14, s86, s14
	s_add_i32 m0, s65, 0xc000
	ds_read_b128 v[148:151], v214
	ds_read_b128 v[152:155], v214 offset:1024
	ds_read_b128 v[156:159], v214 offset:2048
	ds_read_b128 v[172:175], v214 offset:3072
	ds_read_b128 v[176:179], v214 offset:4096
	ds_read_b128 v[180:183], v214 offset:5120
	ds_read_b128 v[184:187], v214 offset:6144
	ds_read_b128 v[188:191], v214 offset:7168
	global_load_lds_dwordx4 v168, s[100:101]
	s_add_i32 m0, s65, 0xe000
	s_nop 0
	global_load_lds_dwordx4 v170, s[100:101]
	s_waitcnt lgkmcnt(8)
	s_barrier
	s_waitcnt lgkmcnt(0)
	s_waitcnt lgkmcnt(0)
	v_mfma_f32_16x16x32_bf16 v[124:127], v[132:135], v[148:151], v[124:127]
	v_mfma_f32_16x16x32_bf16 v[120:123], v[140:143], v[148:151], v[120:123]
	v_mfma_f32_16x16x32_bf16 v[116:119], v[132:135], v[156:159], v[116:119]
	v_mfma_f32_16x16x32_bf16 v[112:115], v[140:143], v[156:159], v[112:115]
	v_mfma_f32_16x16x32_bf16 v[108:111], v[132:135], v[176:179], v[108:111]
	v_mfma_f32_16x16x32_bf16 v[104:107], v[140:143], v[176:179], v[104:107]
	v_mfma_f32_16x16x32_bf16 v[100:103], v[132:135], v[184:187], v[100:103]
	v_mfma_f32_16x16x32_bf16 v[96:99], v[140:143], v[184:187], v[96:99]
	v_mfma_f32_16x16x32_bf16 v[124:127], v[136:139], v[152:155], v[124:127]
	v_mfma_f32_16x16x32_bf16 v[120:123], v[144:147], v[152:155], v[120:123]
	v_mfma_f32_16x16x32_bf16 v[116:119], v[136:139], v[172:175], v[116:119]
	v_mfma_f32_16x16x32_bf16 v[112:115], v[144:147], v[172:175], v[112:115]
	v_mfma_f32_16x16x32_bf16 v[108:111], v[136:139], v[180:183], v[108:111]
	v_mfma_f32_16x16x32_bf16 v[104:107], v[144:147], v[180:183], v[104:107]
	v_mfma_f32_16x16x32_bf16 v[100:103], v[136:139], v[188:191], v[100:103]
	v_mfma_f32_16x16x32_bf16 v[96:99], v[144:147], v[188:191], v[96:99]
	s_barrier
	v_add_u32_e32 v215, 0x14000, v213
	s_add_i32 m0, s64, 0x10000
	ds_read_b128 v[216:219], v215
	ds_read_b128 v[220:223], v215 offset:1024
	ds_read_b128 v[224:227], v215 offset:2048
	ds_read_b128 v[228:231], v215 offset:3072
	global_load_lds_dwordx4 v160, s[14:15]
	s_add_i32 m0, s64, 0x12000
	s_nop 0
	global_load_lds_dwordx4 v166, s[14:15]
	s_barrier
	s_waitcnt lgkmcnt(0)
	s_waitcnt lgkmcnt(0)
	v_mfma_f32_16x16x32_bf16 v[92:95], v[216:219], v[148:151], v[92:95]
	v_mfma_f32_16x16x32_bf16 v[88:91], v[224:227], v[148:151], v[88:91]
	v_mfma_f32_16x16x32_bf16 v[84:87], v[216:219], v[156:159], v[84:87]
	v_mfma_f32_16x16x32_bf16 v[80:83], v[224:227], v[156:159], v[80:83]
	v_mfma_f32_16x16x32_bf16 v[76:79], v[216:219], v[176:179], v[76:79]
	v_mfma_f32_16x16x32_bf16 v[72:75], v[224:227], v[176:179], v[72:75]
	v_mfma_f32_16x16x32_bf16 v[68:71], v[216:219], v[184:187], v[68:71]
	v_mfma_f32_16x16x32_bf16 v[64:67], v[224:227], v[184:187], v[64:67]
	v_mfma_f32_16x16x32_bf16 v[92:95], v[220:223], v[152:155], v[92:95]
	v_mfma_f32_16x16x32_bf16 v[88:91], v[228:231], v[152:155], v[88:91]
	v_mfma_f32_16x16x32_bf16 v[84:87], v[220:223], v[172:175], v[84:87]
	v_mfma_f32_16x16x32_bf16 v[80:83], v[228:231], v[172:175], v[80:83]
	v_mfma_f32_16x16x32_bf16 v[76:79], v[220:223], v[180:183], v[76:79]
	v_mfma_f32_16x16x32_bf16 v[72:75], v[228:231], v[180:183], v[72:75]
	v_mfma_f32_16x16x32_bf16 v[68:71], v[220:223], v[188:191], v[68:71]
	v_mfma_f32_16x16x32_bf16 v[64:67], v[228:231], v[188:191], v[64:67]
	s_mov_b32 m0, s65
	s_barrier
	ds_read_b128 v[148:151], v214 offset:16384
	ds_read_b128 v[152:155], v214 offset:17408
	ds_read_b128 v[156:159], v214 offset:18432
	ds_read_b128 v[172:175], v214 offset:19456
	ds_read_b128 v[176:179], v214 offset:20480
	ds_read_b128 v[180:183], v214 offset:21504
	ds_read_b128 v[184:187], v214 offset:22528
	ds_read_b128 v[188:191], v214 offset:23552
	global_load_lds_dwordx4 v162, s[12:13]
	s_mov_b32 m0, s66
	s_nop 0
	global_load_lds_dwordx4 v164, s[12:13]
	s_barrier
	s_waitcnt lgkmcnt(0)
	s_waitcnt lgkmcnt(0)
	v_mfma_f32_16x16x32_bf16 v[60:63], v[132:135], v[148:151], v[60:63]
	v_mfma_f32_16x16x32_bf16 v[56:59], v[140:143], v[148:151], v[56:59]
	v_mfma_f32_16x16x32_bf16 v[52:55], v[132:135], v[156:159], v[52:55]
	v_mfma_f32_16x16x32_bf16 v[48:51], v[140:143], v[156:159], v[48:51]
	v_mfma_f32_16x16x32_bf16 v[44:47], v[132:135], v[176:179], v[44:47]
	v_mfma_f32_16x16x32_bf16 v[40:43], v[140:143], v[176:179], v[40:43]
	v_mfma_f32_16x16x32_bf16 v[36:39], v[132:135], v[184:187], v[36:39]
	v_mfma_f32_16x16x32_bf16 v[32:35], v[140:143], v[184:187], v[32:35]
	v_mfma_f32_16x16x32_bf16 v[60:63], v[136:139], v[152:155], v[60:63]
	v_mfma_f32_16x16x32_bf16 v[56:59], v[144:147], v[152:155], v[56:59]
	v_mfma_f32_16x16x32_bf16 v[52:55], v[136:139], v[172:175], v[52:55]
	v_mfma_f32_16x16x32_bf16 v[48:51], v[144:147], v[172:175], v[48:51]
	v_mfma_f32_16x16x32_bf16 v[44:47], v[136:139], v[180:183], v[44:47]
	v_mfma_f32_16x16x32_bf16 v[40:43], v[144:147], v[180:183], v[40:43]
	v_mfma_f32_16x16x32_bf16 v[36:39], v[136:139], v[188:191], v[36:39]
	v_mfma_f32_16x16x32_bf16 v[32:35], v[144:147], v[188:191], v[32:35]
	s_barrier
	s_add_u32 s16, s14, s76
	s_addc_u32 s17, s15, s77
	s_add_i32 m0, s64, 0x14000
	s_nop 0
	global_load_lds_dwordx4 v160, s[16:17]
	s_add_i32 m0, s64, 0x16000
	s_nop 0
	global_load_lds_dwordx4 v166, s[16:17]
	s_waitcnt vmcnt(6)
	s_barrier
; #define PG8_STAGE(bufoff, gbase, voff) do { _Pragma("unroll") for (int _i = 0; _i < 2; ++_i) \
;         __builtin_amdgcn_global_load_lds((const unsigned*)((const char*)(gbase) + (voff)[_i]), (LAS unsigned*)(lds + (bufoff) + ldsw + _i * 8192), 16, 0, 0); } while (0)
; #define PG8_LDA(dst, b, h) do { _Pragma("unroll") for (int m = 0; m < 4; ++m) _Pragma("unroll") for (int k = 0; k < 2; ++k) dst[m][k] = *(const LAS bf16x8*)(lds + PG8_SA(b, h) + aoff + m * 2048 + k * 1024); } while (0)
; #define PG8_LDB(dst, b, h) do { _Pragma("unroll") for (int n = 0; n < 2; ++n) _Pragma("unroll") for (int k = 0; k < 2; ++k) dst[n][k] = *(const LAS bf16x8*)(lds + PG8_SB(b, h) + boff + n * 2048 + k * 1024); } while (0)
; #define PG8_MMA(ai, bj, At, Bt) do { __builtin_amdgcn_s_setprio(1); _Pragma("unroll") for (int m = 0; m < 4; ++m) _Pragma("unroll") for (int n = 0; n < 2; ++n) _Pragma("unroll") for (int k = 0; k < 2; ++k) \
;         acc[ai][bj][m][n] = __builtin_amdgcn_mfma_f32_16x16x32_bf16(Bt[n][k], At[m][k], acc[ai][bj][m][n], 0, 0, 0); __builtin_amdgcn_s_setprio(0); } while (0)
; #define PG8_WAIT_V(n) asm volatile("s_waitcnt vmcnt(" #n ")" ::: "memory")
; #define PG8_WAIT_L(n) asm volatile("s_waitcnt lgkmcnt(" #n ")" ::: "memory")
; #define PG8_BAR __builtin_amdgcn_s_barrier()
; #define PG8_SCHED __builtin_amdgcn_sched_barrier(0)
; __device__ __forceinline__ void gemm_phase(LAS unsigned char* lds, CParams& p, const Job& jb) {
;     ...
;             PG8_WAIT_V(6); PG8_BAR; PG8_MMA(1, 1, At, B1); PG8_BAR;
;             PG8_LDB(B0, 1, 0); PG8_SCHED; PG8_LDA(At, 1, 0); PG8_STAGE(PG8_SA(0, 1), a2 + hstepA, voffA);
;             PG8_WAIT_L(8); PG8_BAR; PG8_WAIT_L(0); PG8_MMA(0, 0, At, B0); PG8_BAR; PG8_SCHED;
;             PG8_LDB(B1, 1, 1); PG8_STAGE(PG8_SB(1, 0), b3, voffB);
;             PG8_BAR; PG8_WAIT_L(0); PG8_MMA(0, 1, At, B1); PG8_BAR;
;             PG8_LDA(At, 1, 1); PG8_STAGE(PG8_SA(1, 0), a3, voffA);
	v_mfma_f32_16x16x32_bf16 v[28:31], v[216:219], v[148:151], v[28:31]
	v_mfma_f32_16x16x32_bf16 v[24:27], v[224:227], v[148:151], v[24:27]
	v_mfma_f32_16x16x32_bf16 v[20:23], v[216:219], v[156:159], v[20:23]
	v_mfma_f32_16x16x32_bf16 v[16:19], v[224:227], v[156:159], v[16:19]
	v_mfma_f32_16x16x32_bf16 v[12:15], v[216:219], v[176:179], v[12:15]
	v_mfma_f32_16x16x32_bf16 v[8:11], v[224:227], v[176:179], v[8:11]
	v_mfma_f32_16x16x32_bf16 v[4:7], v[216:219], v[184:187], v[4:7]
	v_mfma_f32_16x16x32_bf16 v[0:3], v[224:227], v[184:187], v[0:3]
	v_mfma_f32_16x16x32_bf16 v[28:31], v[220:223], v[152:155], v[28:31]
	v_mfma_f32_16x16x32_bf16 v[24:27], v[228:231], v[152:155], v[24:27]
	v_mfma_f32_16x16x32_bf16 v[20:23], v[220:223], v[172:175], v[20:23]
	v_mfma_f32_16x16x32_bf16 v[16:19], v[228:231], v[172:175], v[16:19]
	v_mfma_f32_16x16x32_bf16 v[12:15], v[220:223], v[180:183], v[12:15]
	v_mfma_f32_16x16x32_bf16 v[8:11], v[228:231], v[180:183], v[8:11]
	v_mfma_f32_16x16x32_bf16 v[4:7], v[220:223], v[188:191], v[4:7]
	v_mfma_f32_16x16x32_bf16 v[0:3], v[228:231], v[188:191], v[0:3]
	v_add_u32_e32 v144, 0x18000, v213
	s_barrier
	ds_read_b128 v[132:135], v144
	ds_read_b128 v[136:139], v144 offset:1024
	ds_read_b128 v[140:143], v144 offset:2048
	ds_read_b128 v[144:147], v144 offset:3072
	s_add_u32 s100, s12, s74
	s_addc_u32 s101, s13, s75
	s_mov_b32 m0, s67
	ds_read_b128 v[148:151], v214 offset:32768
	ds_read_b128 v[152:155], v214 offset:33792
	ds_read_b128 v[156:159], v214 offset:34816
	ds_read_b128 v[172:175], v214 offset:35840
	ds_read_b128 v[176:179], v214 offset:36864
	ds_read_b128 v[180:183], v214 offset:37888
	ds_read_b128 v[184:187], v214 offset:38912
	ds_read_b128 v[188:191], v214 offset:39936
	global_load_lds_dwordx4 v162, s[100:101]
	s_mov_b32 m0, s94
	s_nop 0
	global_load_lds_dwordx4 v164, s[100:101]
	s_waitcnt lgkmcnt(8)
	s_barrier
	s_waitcnt lgkmcnt(0)
	s_waitcnt lgkmcnt(0)
	v_mfma_f32_16x16x32_bf16 v[124:127], v[132:135], v[148:151], v[124:127]
	v_mfma_f32_16x16x32_bf16 v[120:123], v[140:143], v[148:151], v[120:123]
	v_mfma_f32_16x16x32_bf16 v[116:119], v[132:135], v[156:159], v[116:119]
	v_mfma_f32_16x16x32_bf16 v[112:115], v[140:143], v[156:159], v[112:115]
	v_mfma_f32_16x16x32_bf16 v[108:111], v[132:135], v[176:179], v[108:111]
	v_mfma_f32_16x16x32_bf16 v[104:107], v[140:143], v[176:179], v[104:107]
	v_mfma_f32_16x16x32_bf16 v[100:103], v[132:135], v[184:187], v[100:103]
	v_mfma_f32_16x16x32_bf16 v[96:99], v[140:143], v[184:187], v[96:99]
	v_mfma_f32_16x16x32_bf16 v[124:127], v[136:139], v[152:155], v[124:127]
	v_mfma_f32_16x16x32_bf16 v[120:123], v[144:147], v[152:155], v[120:123]
	v_mfma_f32_16x16x32_bf16 v[116:119], v[136:139], v[172:175], v[116:119]
	v_mfma_f32_16x16x32_bf16 v[112:115], v[144:147], v[172:175], v[112:115]
	v_mfma_f32_16x16x32_bf16 v[108:111], v[136:139], v[180:183], v[108:111]
	v_mfma_f32_16x16x32_bf16 v[104:107], v[144:147], v[180:183], v[104:107]
	v_mfma_f32_16x16x32_bf16 v[100:103], v[136:139], v[188:191], v[100:103]
	v_mfma_f32_16x16x32_bf16 v[96:99], v[144:147], v[188:191], v[96:99]
	s_barrier
	v_add_u32_e32 v215, 0x1c000, v213
	s_add_u32 s14, s14, s90
	s_addc_u32 s15, s15, s91
	s_add_i32 m0, s64, 0x18000
	ds_read_b128 v[216:219], v215
	ds_read_b128 v[220:223], v215 offset:1024
	ds_read_b128 v[224:227], v215 offset:2048
	ds_read_b128 v[228:231], v215 offset:3072
	global_load_lds_dwordx4 v160, s[14:15]
	s_add_i32 m0, s64, 0x1a000
	s_nop 0
	global_load_lds_dwordx4 v166, s[14:15]
	s_barrier
	s_waitcnt lgkmcnt(0)
	s_waitcnt lgkmcnt(0)
	v_mfma_f32_16x16x32_bf16 v[92:95], v[216:219], v[148:151], v[92:95]
	v_mfma_f32_16x16x32_bf16 v[88:91], v[224:227], v[148:151], v[88:91]
	v_mfma_f32_16x16x32_bf16 v[84:87], v[216:219], v[156:159], v[84:87]
	v_mfma_f32_16x16x32_bf16 v[80:83], v[224:227], v[156:159], v[80:83]
	v_mfma_f32_16x16x32_bf16 v[76:79], v[216:219], v[176:179], v[76:79]
	v_mfma_f32_16x16x32_bf16 v[72:75], v[224:227], v[176:179], v[72:75]
	v_mfma_f32_16x16x32_bf16 v[68:71], v[216:219], v[184:187], v[68:71]
	v_mfma_f32_16x16x32_bf16 v[64:67], v[224:227], v[184:187], v[64:67]
	v_mfma_f32_16x16x32_bf16 v[92:95], v[220:223], v[152:155], v[92:95]
	v_mfma_f32_16x16x32_bf16 v[88:91], v[228:231], v[152:155], v[88:91]
	v_mfma_f32_16x16x32_bf16 v[84:87], v[220:223], v[172:175], v[84:87]
	v_mfma_f32_16x16x32_bf16 v[80:83], v[228:231], v[172:175], v[80:83]
	v_mfma_f32_16x16x32_bf16 v[76:79], v[220:223], v[180:183], v[76:79]
	v_mfma_f32_16x16x32_bf16 v[72:75], v[228:231], v[180:183], v[72:75]
	v_mfma_f32_16x16x32_bf16 v[68:71], v[220:223], v[188:191], v[68:71]
	v_mfma_f32_16x16x32_bf16 v[64:67], v[228:231], v[188:191], v[64:67]
	s_mov_b32 m0, s33
	s_add_u32 s12, s12, s90
	s_addc_u32 s13, s13, s91
	s_barrier
	ds_read_b128 v[148:151], v214 offset:49152
	ds_read_b128 v[152:155], v214 offset:50176
	ds_read_b128 v[156:159], v214 offset:51200
	ds_read_b128 v[172:175], v214 offset:52224
	ds_read_b128 v[176:179], v214 offset:53248
	ds_read_b128 v[180:183], v214 offset:54272
	ds_read_b128 v[184:187], v214 offset:55296
	ds_read_b128 v[188:191], v214 offset:56320
	global_load_lds_dwordx4 v162, s[12:13]
	s_mov_b32 m0, s60
	s_nop 0
	global_load_lds_dwordx4 v164, s[12:13]
	s_barrier
; #define FOR_ROWS _Pragma("unroll") for (int ai = 0; ai < 2; ++ai) _Pragma("unroll") for (int m = 0; m < 4; ++m)
; #define PG8_STAGE(bufoff, gbase, voff) do { _Pragma("unroll") for (int _i = 0; _i < 2; ++_i) \
;         __builtin_amdgcn_global_load_lds((const unsigned*)((const char*)(gbase) + (voff)[_i]), (LAS unsigned*)(lds + (bufoff) + ldsw + _i * 8192), 16, 0, 0); } while (0)
; #define PG8_MMA(ai, bj, At, Bt) do { __builtin_amdgcn_s_setprio(1); _Pragma("unroll") for (int m = 0; m < 4; ++m) _Pragma("unroll") for (int n = 0; n < 2; ++n) _Pragma("unroll") for (int k = 0; k < 2; ++k) \
;         acc[ai][bj][m][n] = __builtin_amdgcn_mfma_f32_16x16x32_bf16(Bt[n][k], At[m][k], acc[ai][bj][m][n], 0, 0, 0); __builtin_amdgcn_s_setprio(0); } while (0)
; #define PG8_WAIT_V(n) asm volatile("s_waitcnt vmcnt(" #n ")" ::: "memory")
; #define PG8_WAIT_L(n) asm volatile("s_waitcnt lgkmcnt(" #n ")" ::: "memory")
; #define PG8_BAR __builtin_amdgcn_s_barrier()
; #define PG8_SCHED __builtin_amdgcn_sched_barrier(0)
; __device__ __forceinline__ void epilogue(const int kind, CParams& p, const f32x4 (&acc)[2][2][4][2], const Unit& u, const int wr, const int wc, const int fr_in, const int fq_in) {
;     ...
;     case E_DOWN_HALF: {
;         FOR_ROWS { ROWDEF
; #pragma unroll
;             for (int bj = 0; bj < 2; ++bj) { float* hp = p.out + row * 1024 + u.pn * 256 + bj * 128 + cw;
; #pragma unroll
;                 for (int j = 0; j < 4; ++j) { unsafeAtomicAdd(hp + j, acc[ai][bj][m][0][j]); unsafeAtomicAdd(hp + 4 + j, acc[ai][bj][m][1][j]); } } }
;     } break;
; __device__ __forceinline__ void gemm_phase(LAS unsigned char* lds, CParams& p, const Job& jb) {
;     ...
;             PG8_BAR; PG8_WAIT_L(0); PG8_MMA(1, 0, At, B0); PG8_BAR; PG8_SCHED;
;             PG8_STAGE(PG8_SB(1, 1), b3 + hstepB, voffB);
;             PG8_WAIT_V(6); PG8_BAR; PG8_MMA(1, 1, At, B1); PG8_BAR;
;         }
;         epilogue(cur.kind, p, acc, cur, wr, wc, fr, fq);
	s_waitcnt lgkmcnt(0)
	s_waitcnt lgkmcnt(0)
	v_mfma_f32_16x16x32_bf16 v[60:63], v[132:135], v[148:151], v[60:63]
	v_mfma_f32_16x16x32_bf16 v[56:59], v[140:143], v[148:151], v[56:59]
	v_mfma_f32_16x16x32_bf16 v[52:55], v[132:135], v[156:159], v[52:55]
	v_mfma_f32_16x16x32_bf16 v[48:51], v[140:143], v[156:159], v[48:51]
	v_mfma_f32_16x16x32_bf16 v[44:47], v[132:135], v[176:179], v[44:47]
	v_mfma_f32_16x16x32_bf16 v[40:43], v[140:143], v[176:179], v[40:43]
	v_mfma_f32_16x16x32_bf16 v[36:39], v[132:135], v[184:187], v[36:39]
	v_mfma_f32_16x16x32_bf16 v[32:35], v[140:143], v[184:187], v[32:35]
	v_mfma_f32_16x16x32_bf16 v[60:63], v[136:139], v[152:155], v[60:63]
	v_mfma_f32_16x16x32_bf16 v[56:59], v[144:147], v[152:155], v[56:59]
	v_mfma_f32_16x16x32_bf16 v[52:55], v[136:139], v[172:175], v[52:55]
	v_mfma_f32_16x16x32_bf16 v[48:51], v[144:147], v[172:175], v[48:51]
	v_mfma_f32_16x16x32_bf16 v[44:47], v[136:139], v[180:183], v[44:47]
	v_mfma_f32_16x16x32_bf16 v[40:43], v[144:147], v[180:183], v[40:43]
	v_mfma_f32_16x16x32_bf16 v[36:39], v[136:139], v[188:191], v[36:39]
	v_mfma_f32_16x16x32_bf16 v[32:35], v[144:147], v[188:191], v[32:35]
	s_barrier
	s_add_u32 s16, s16, s90
	s_addc_u32 s17, s17, s91
	s_add_i32 m0, s64, 0x1c000
	s_nop 0
	global_load_lds_dwordx4 v160, s[16:17]
	s_add_i32 m0, s64, 0x1e000
	s_nop 0
	global_load_lds_dwordx4 v166, s[16:17]
	s_waitcnt vmcnt(6)
	s_barrier
	v_mfma_f32_16x16x32_bf16 v[28:31], v[216:219], v[148:151], v[28:31]
	v_mfma_f32_16x16x32_bf16 v[24:27], v[224:227], v[148:151], v[24:27]
	v_mfma_f32_16x16x32_bf16 v[20:23], v[216:219], v[156:159], v[20:23]
	v_mfma_f32_16x16x32_bf16 v[16:19], v[224:227], v[156:159], v[16:19]
	v_mfma_f32_16x16x32_bf16 v[12:15], v[216:219], v[176:179], v[12:15]
	v_mfma_f32_16x16x32_bf16 v[8:11], v[224:227], v[176:179], v[8:11]
	v_mfma_f32_16x16x32_bf16 v[4:7], v[216:219], v[184:187], v[4:7]
	v_mfma_f32_16x16x32_bf16 v[0:3], v[224:227], v[184:187], v[0:3]
	v_mfma_f32_16x16x32_bf16 v[28:31], v[220:223], v[152:155], v[28:31]
	v_mfma_f32_16x16x32_bf16 v[24:27], v[228:231], v[152:155], v[24:27]
	v_mfma_f32_16x16x32_bf16 v[20:23], v[220:223], v[172:175], v[20:23]
	v_mfma_f32_16x16x32_bf16 v[16:19], v[228:231], v[172:175], v[16:19]
	v_mfma_f32_16x16x32_bf16 v[12:15], v[220:223], v[180:183], v[12:15]
	v_mfma_f32_16x16x32_bf16 v[8:11], v[228:231], v[180:183], v[8:11]
	v_mfma_f32_16x16x32_bf16 v[4:7], v[220:223], v[188:191], v[4:7]
	v_mfma_f32_16x16x32_bf16 v[0:3], v[228:231], v[188:191], v[0:3]
	s_add_u32 s10, s10, 0x100
	s_addc_u32 s11, s11, 0
	s_cmp_ge_u32 s1, s84
	s_barrier
	s_cbranch_scc0 .LBB0_631
	v_mov_b32_e32 v215, v211
	v_mov_b32_e32 v216, v212
	s_cmp_eq_u32 s3, 13
	s_cbranch_scc1 .Lmy_down
	s_cmp_eq_u32 s3, 12
	s_cbranch_scc1 .Lmy_ffn1
	s_cmp_lt_i32 s3, 7
	v_lshl_add_u32 v172, v216, 3, s31
	s_mov_b64 s[10:11], -1
	s_cbranch_scc1 .LBB0_849
	s_cmp_lt_i32 s3, 11
	s_cbranch_scc1 .LBB0_639
	s_cmp_gt_i32 s3, 12
	s_cbranch_scc0 .LBB0_640
	s_cmp_gt_i32 s3, 13
	s_mov_b64 s[26:27], -1
	s_cbranch_scc0 .LBB0_641
	s_cmp_eq_u32 s3, 14
	s_cbranch_scc0 .LBB0_638
	v_add_u32_e32 v128, s0, v215
	s_ashr_i32 s79, s78, 31
	v_ashrrev_i32_e32 v129, 31, v128
	v_lshl_add_u64 v[130:131], v[128:129], 0, s[78:79]
	s_lshl_b32 s10, s92, 8
	v_lshlrev_b64 v[130:131], 12, v[130:131]
	s_ashr_i32 s11, s10, 31
	v_ashrrev_i32_e32 v173, 31, v172
	v_lshl_add_u64 v[130:131], s[82:83], 0, v[130:131]
	s_lshl_b64 s[10:11], s[10:11], 2
	v_lshl_add_u64 v[130:131], v[130:131], 0, s[10:11]
	v_lshlrev_b64 v[132:133], 2, v[172:173]
	v_lshl_add_u64 v[130:131], v[130:131], 0, v[132:133]
	global_atomic_add_f32 v[130:131], v124, off
	global_atomic_add_f32 v[130:131], v120, off offset:16
	global_atomic_add_f32 v[130:131], v125, off offset:4
	global_atomic_add_f32 v[130:131], v121, off offset:20
	global_atomic_add_f32 v[130:131], v126, off offset:8
	global_atomic_add_f32 v[130:131], v122, off offset:24
	global_atomic_add_f32 v[130:131], v127, off offset:12
	global_atomic_add_f32 v[130:131], v123, off offset:28
	global_atomic_add_f32 v[130:131], v92, off offset:512
	global_atomic_add_f32 v[130:131], v88, off offset:528
	global_atomic_add_f32 v[130:131], v93, off offset:516
	global_atomic_add_f32 v[130:131], v89, off offset:532
	global_atomic_add_f32 v[130:131], v94, off offset:520
	global_atomic_add_f32 v[130:131], v90, off offset:536
	global_atomic_add_f32 v[130:131], v95, off offset:524
	global_atomic_add_f32 v[130:131], v91, off offset:540
	v_add_u32_e32 v130, 16, v128
	v_ashrrev_i32_e32 v131, 31, v130
	v_lshl_add_u64 v[130:131], v[130:131], 0, s[78:79]
	v_lshlrev_b64 v[130:131], 12, v[130:131]
	v_lshl_add_u64 v[130:131], s[82:83], 0, v[130:131]
	v_lshl_add_u64 v[130:131], v[130:131], 0, s[10:11]
	v_lshl_add_u64 v[130:131], v[130:131], 0, v[132:133]
	global_atomic_add_f32 v[130:131], v116, off
	global_atomic_add_f32 v[130:131], v112, off offset:16
	global_atomic_add_f32 v[130:131], v117, off offset:4
	global_atomic_add_f32 v[130:131], v113, off offset:20
	global_atomic_add_f32 v[130:131], v118, off offset:8
	global_atomic_add_f32 v[130:131], v114, off offset:24
	global_atomic_add_f32 v[130:131], v119, off offset:12
	global_atomic_add_f32 v[130:131], v115, off offset:28
	global_atomic_add_f32 v[130:131], v84, off offset:512
	global_atomic_add_f32 v[130:131], v80, off offset:528
	global_atomic_add_f32 v[130:131], v85, off offset:516
	global_atomic_add_f32 v[130:131], v81, off offset:532
	global_atomic_add_f32 v[130:131], v86, off offset:520
	global_atomic_add_f32 v[130:131], v82, off offset:536
	global_atomic_add_f32 v[130:131], v87, off offset:524
	global_atomic_add_f32 v[130:131], v83, off offset:540
	v_add_u32_e32 v130, 32, v128
; #define FOR_ROWS _Pragma("unroll") for (int ai = 0; ai < 2; ++ai) _Pragma("unroll") for (int m = 0; m < 4; ++m)
; __device__ __forceinline__ void epilogue(const int kind, CParams& p, const f32x4 (&acc)[2][2][4][2], const Unit& u, const int wr, const int wc, const int fr_in, const int fq_in) {
;     ...
;     case E_DOWN_HALF: {
;         FOR_ROWS { ROWDEF
; #pragma unroll
;             for (int bj = 0; bj < 2; ++bj) { float* hp = p.out + row * 1024 + u.pn * 256 + bj * 128 + cw;
; #pragma unroll
;                 for (int j = 0; j < 4; ++j) { unsafeAtomicAdd(hp + j, acc[ai][bj][m][0][j]); unsafeAtomicAdd(hp + 4 + j, acc[ai][bj][m][1][j]); } } }
;     } break;
	v_ashrrev_i32_e32 v131, 31, v130
	v_lshl_add_u64 v[130:131], v[130:131], 0, s[78:79]
	v_lshlrev_b64 v[130:131], 12, v[130:131]
	v_lshl_add_u64 v[130:131], s[82:83], 0, v[130:131]
	v_lshl_add_u64 v[130:131], v[130:131], 0, s[10:11]
	v_lshl_add_u64 v[130:131], v[130:131], 0, v[132:133]
	global_atomic_add_f32 v[130:131], v108, off
	global_atomic_add_f32 v[130:131], v104, off offset:16
	global_atomic_add_f32 v[130:131], v109, off offset:4
	global_atomic_add_f32 v[130:131], v105, off offset:20
	global_atomic_add_f32 v[130:131], v110, off offset:8
	global_atomic_add_f32 v[130:131], v106, off offset:24
	global_atomic_add_f32 v[130:131], v111, off offset:12
	global_atomic_add_f32 v[130:131], v107, off offset:28
	global_atomic_add_f32 v[130:131], v76, off offset:512
	global_atomic_add_f32 v[130:131], v72, off offset:528
	global_atomic_add_f32 v[130:131], v77, off offset:516
	global_atomic_add_f32 v[130:131], v73, off offset:532
	global_atomic_add_f32 v[130:131], v78, off offset:520
	global_atomic_add_f32 v[130:131], v74, off offset:536
	global_atomic_add_f32 v[130:131], v79, off offset:524
	global_atomic_add_f32 v[130:131], v75, off offset:540
	v_add_u32_e32 v130, 48, v128
	v_ashrrev_i32_e32 v131, 31, v130
	v_lshl_add_u64 v[130:131], v[130:131], 0, s[78:79]
	v_lshlrev_b64 v[130:131], 12, v[130:131]
	v_lshl_add_u64 v[130:131], s[82:83], 0, v[130:131]
	v_lshl_add_u64 v[130:131], v[130:131], 0, s[10:11]
	v_lshl_add_u64 v[130:131], v[130:131], 0, v[132:133]
	global_atomic_add_f32 v[130:131], v100, off
	global_atomic_add_f32 v[130:131], v96, off offset:16
	global_atomic_add_f32 v[130:131], v101, off offset:4
	global_atomic_add_f32 v[130:131], v97, off offset:20
	global_atomic_add_f32 v[130:131], v102, off offset:8
	global_atomic_add_f32 v[130:131], v98, off offset:24
	global_atomic_add_f32 v[130:131], v103, off offset:12
	global_atomic_add_f32 v[130:131], v99, off offset:28
	global_atomic_add_f32 v[130:131], v68, off offset:512
	global_atomic_add_f32 v[130:131], v64, off offset:528
	global_atomic_add_f32 v[130:131], v69, off offset:516
	global_atomic_add_f32 v[130:131], v65, off offset:532
	global_atomic_add_f32 v[130:131], v70, off offset:520
	global_atomic_add_f32 v[130:131], v66, off offset:536
	global_atomic_add_f32 v[130:131], v71, off offset:524
	global_atomic_add_f32 v[130:131], v67, off offset:540
	v_add_u32_e32 v130, 0x80, v128
	v_ashrrev_i32_e32 v131, 31, v130
	v_lshl_add_u64 v[130:131], v[130:131], 0, s[78:79]
	v_lshlrev_b64 v[130:131], 12, v[130:131]
	v_lshl_add_u64 v[130:131], s[82:83], 0, v[130:131]
	v_lshl_add_u64 v[130:131], v[130:131], 0, s[10:11]
	v_lshl_add_u64 v[130:131], v[130:131], 0, v[132:133]
	global_atomic_add_f32 v[130:131], v60, off
	global_atomic_add_f32 v[130:131], v56, off offset:16
	global_atomic_add_f32 v[130:131], v61, off offset:4
	global_atomic_add_f32 v[130:131], v57, off offset:20
	global_atomic_add_f32 v[130:131], v62, off offset:8
	global_atomic_add_f32 v[130:131], v58, off offset:24
	global_atomic_add_f32 v[130:131], v63, off offset:12
	global_atomic_add_f32 v[130:131], v59, off offset:28
	global_atomic_add_f32 v[130:131], v28, off offset:512
	global_atomic_add_f32 v[130:131], v24, off offset:528
	global_atomic_add_f32 v[130:131], v29, off offset:516
	global_atomic_add_f32 v[130:131], v25, off offset:532
	global_atomic_add_f32 v[130:131], v30, off offset:520
	global_atomic_add_f32 v[130:131], v26, off offset:536
	global_atomic_add_f32 v[130:131], v31, off offset:524
	global_atomic_add_f32 v[130:131], v27, off offset:540
	v_add_u32_e32 v130, 0x90, v128
	v_ashrrev_i32_e32 v131, 31, v130
	v_lshl_add_u64 v[130:131], v[130:131], 0, s[78:79]
	v_lshlrev_b64 v[130:131], 12, v[130:131]
	v_lshl_add_u64 v[130:131], s[82:83], 0, v[130:131]
	v_lshl_add_u64 v[130:131], v[130:131], 0, s[10:11]
	v_lshl_add_u64 v[130:131], v[130:131], 0, v[132:133]
	global_atomic_add_f32 v[130:131], v52, off
	global_atomic_add_f32 v[130:131], v48, off offset:16
	global_atomic_add_f32 v[130:131], v53, off offset:4
	global_atomic_add_f32 v[130:131], v49, off offset:20
	global_atomic_add_f32 v[130:131], v54, off offset:8
	global_atomic_add_f32 v[130:131], v50, off offset:24
	global_atomic_add_f32 v[130:131], v55, off offset:12
	global_atomic_add_f32 v[130:131], v51, off offset:28
	global_atomic_add_f32 v[130:131], v20, off offset:512
	global_atomic_add_f32 v[130:131], v16, off offset:528
	global_atomic_add_f32 v[130:131], v21, off offset:516
	global_atomic_add_f32 v[130:131], v17, off offset:532
	global_atomic_add_f32 v[130:131], v22, off offset:520
	global_atomic_add_f32 v[130:131], v18, off offset:536
	global_atomic_add_f32 v[130:131], v23, off offset:524
	global_atomic_add_f32 v[130:131], v19, off offset:540
	v_add_u32_e32 v130, 0xa0, v128
	v_ashrrev_i32_e32 v131, 31, v130
	v_add_u32_e32 v128, 0xb0, v128
	v_lshl_add_u64 v[130:131], v[130:131], 0, s[78:79]
	v_ashrrev_i32_e32 v129, 31, v128
	v_lshlrev_b64 v[130:131], 12, v[130:131]
	v_lshl_add_u64 v[128:129], v[128:129], 0, s[78:79]
	v_lshl_add_u64 v[130:131], s[82:83], 0, v[130:131]
	v_lshlrev_b64 v[128:129], 12, v[128:129]
	v_lshl_add_u64 v[130:131], v[130:131], 0, s[10:11]
	v_lshl_add_u64 v[128:129], s[82:83], 0, v[128:129]
	v_lshl_add_u64 v[130:131], v[130:131], 0, v[132:133]
	v_lshl_add_u64 v[128:129], v[128:129], 0, s[10:11]
	global_atomic_add_f32 v[130:131], v44, off
	global_atomic_add_f32 v[130:131], v40, off offset:16
	global_atomic_add_f32 v[130:131], v45, off offset:4
	global_atomic_add_f32 v[130:131], v41, off offset:20
	global_atomic_add_f32 v[130:131], v46, off offset:8
	global_atomic_add_f32 v[130:131], v42, off offset:24
	global_atomic_add_f32 v[130:131], v47, off offset:12
	global_atomic_add_f32 v[130:131], v43, off offset:28
	global_atomic_add_f32 v[130:131], v12, off offset:512
	global_atomic_add_f32 v[130:131], v8, off offset:528
	global_atomic_add_f32 v[130:131], v13, off offset:516
	global_atomic_add_f32 v[130:131], v9, off offset:532
	global_atomic_add_f32 v[130:131], v14, off offset:520
	global_atomic_add_f32 v[130:131], v10, off offset:536
	global_atomic_add_f32 v[130:131], v15, off offset:524
	global_atomic_add_f32 v[130:131], v11, off offset:540
	v_lshl_add_u64 v[128:129], v[128:129], 0, v[132:133]
	global_atomic_add_f32 v[128:129], v36, off
	global_atomic_add_f32 v[128:129], v32, off offset:16
	global_atomic_add_f32 v[128:129], v37, off offset:4
	global_atomic_add_f32 v[128:129], v33, off offset:20
	global_atomic_add_f32 v[128:129], v38, off offset:8
	global_atomic_add_f32 v[128:129], v34, off offset:24
	global_atomic_add_f32 v[128:129], v39, off offset:12
	global_atomic_add_f32 v[128:129], v35, off offset:28
	global_atomic_add_f32 v[128:129], v4, off offset:512
	global_atomic_add_f32 v[128:129], v0, off offset:528
	global_atomic_add_f32 v[128:129], v5, off offset:516
	global_atomic_add_f32 v[128:129], v1, off offset:532
	global_atomic_add_f32 v[128:129], v6, off offset:520
	global_atomic_add_f32 v[128:129], v2, off offset:536
	global_atomic_add_f32 v[128:129], v7, off offset:524
	global_atomic_add_f32 v[128:129], v3, off offset:540
